# non-temporal hint on single-use streams: norm0 x loads (16) and final-norm f32 output stores (4); size-neutral
# baseline (speedup 1.0000x reference)
.LBB0_326:
	s_and_b64 vcc, exec, s[18:19]
	s_cbranch_vccz .LBB0_317
	global_store_dwordx4 v[54:55], v[28:31], off nt
	global_store_dwordx4 v[54:55], v[24:27], off offset:16 nt
	global_store_dwordx4 v[54:55], v[20:23], off offset:2048 nt
	global_store_dwordx4 v[54:55], v[16:19], off offset:2064 nt
	s_branch .LBB0_317

.Ln0_loop:
	s_add_i32 s15, s14, s24
	s_cmp_lt_u32 s15, 0xc000
	s_cselect_b32 s47, s15, s14
	s_add_i32 s15, s15, s24
	s_cmp_lt_u32 s15, 0xc000
	s_cselect_b32 s34, s15, s14
	s_add_i32 s15, s15, s24
	s_cmp_lt_u32 s15, 0xc000
	s_cselect_b32 s35, s15, s14
	s_add_i32 s15, s15, s24
	s_cmp_lt_u32 s14, 0x4000
	s_cselect_b32 s0, s36, s38
	s_cselect_b32 s1, s37, s39
	s_cselect_b32 s12, 0, 0x4000
	s_sub_u32 s12, s14, s12
	s_lshl_b32 s12, s12, 12
	s_add_u32 s0, s0, s12
	s_addc_u32 s1, s1, 0
	global_load_dwordx4 v[32:35], v2, s[0:1] nt
	global_load_dwordx4 v[36:39], v2, s[0:1] offset:16 nt
	global_load_dwordx4 v[40:43], v2, s[0:1] offset:2048 nt
	global_load_dwordx4 v[44:47], v2, s[0:1] offset:2064 nt
	s_cmp_lt_u32 s47, 0x4000
	s_cselect_b32 s0, s36, s38
	s_cselect_b32 s1, s37, s39
	s_cselect_b32 s12, 0, 0x4000
	s_sub_u32 s12, s47, s12
	s_lshl_b32 s12, s12, 12
	s_add_u32 s0, s0, s12
	s_addc_u32 s1, s1, 0
	global_load_dwordx4 v[48:51], v2, s[0:1] nt
	global_load_dwordx4 v[52:55], v2, s[0:1] offset:16 nt
	global_load_dwordx4 v[56:59], v2, s[0:1] offset:2048 nt
	global_load_dwordx4 v[60:63], v2, s[0:1] offset:2064 nt
	s_cmp_lt_u32 s34, 0x4000
	s_cselect_b32 s0, s36, s38
	s_cselect_b32 s1, s37, s39
	s_cselect_b32 s12, 0, 0x4000
	s_sub_u32 s12, s34, s12
	s_lshl_b32 s12, s12, 12
	s_add_u32 s0, s0, s12
	s_addc_u32 s1, s1, 0
	global_load_dwordx4 v[64:67], v2, s[0:1] nt
	global_load_dwordx4 v[68:71], v2, s[0:1] offset:16 nt
	global_load_dwordx4 v[72:75], v2, s[0:1] offset:2048 nt
	global_load_dwordx4 v[76:79], v2, s[0:1] offset:2064 nt
	s_cmp_lt_u32 s35, 0x4000
	s_cselect_b32 s0, s36, s38
	s_cselect_b32 s1, s37, s39
	s_cselect_b32 s12, 0, 0x4000
	s_sub_u32 s12, s35, s12
	s_lshl_b32 s12, s12, 12
	s_add_u32 s0, s0, s12
	s_addc_u32 s1, s1, 0
	global_load_dwordx4 v[80:83], v2, s[0:1] nt
	global_load_dwordx4 v[84:87], v2, s[0:1] offset:16 nt
	global_load_dwordx4 v[88:91], v2, s[0:1] offset:2048 nt
	global_load_dwordx4 v[92:95], v2, s[0:1] offset:2064 nt
	s_lshl_b32 s12, s14, 11
	s_add_u32 s4, s40, s12
	s_addc_u32 s5, s41, 0
	s_lshl_b32 s12, s47, 11
	s_add_u32 s50, s40, s12
	s_addc_u32 s51, s41, 0
	s_lshl_b32 s12, s34, 11
	s_add_u32 s18, s40, s12
	s_addc_u32 s19, s41, 0
	s_lshl_b32 s12, s35, 11
	s_add_u32 s30, s40, s12
	s_addc_u32 s31, s41, 0
	s_waitcnt vmcnt(0)
	v_pk_mul_f32 v[106:107], v[32:33], v[32:33]
	v_pk_mul_f32 v[108:109], v[34:35], v[34:35]
	v_add_f32_e32 v104, v106, v107
	v_add_f32_e32 v104, v104, v108
	v_pk_mul_f32 v[110:111], v[36:37], v[36:37]
	v_add_f32_e32 v104, v104, v109
	v_add_f32_e32 v104, v104, v110
	v_pk_mul_f32 v[112:113], v[38:39], v[38:39]
	v_add_f32_e32 v104, v104, v111
	v_add_f32_e32 v104, v104, v112
	v_add_f32_e32 v104, v104, v113
	v_pk_mul_f32 v[106:107], v[40:41], v[40:41]
	v_pk_mul_f32 v[108:109], v[42:43], v[42:43]
	v_add_f32_e32 v105, v106, v107
	v_add_f32_e32 v105, v105, v108
	v_pk_mul_f32 v[110:111], v[44:45], v[44:45]
	v_add_f32_e32 v105, v105, v109
	v_add_f32_e32 v105, v105, v110
	v_pk_mul_f32 v[112:113], v[46:47], v[46:47]
	v_add_f32_e32 v105, v105, v111
	v_add_f32_e32 v105, v105, v112
	v_add_f32_e32 v105, v105, v113
	v_add_f32_e32 v96, v104, v105
	v_cvt_pk_bf16_f32 v32, v32, v33
	v_cvt_pk_bf16_f32 v33, v34, v35
	v_cvt_pk_bf16_f32 v34, v36, v37
	v_cvt_pk_bf16_f32 v35, v38, v39
	v_cvt_pk_bf16_f32 v40, v40, v41
	v_cvt_pk_bf16_f32 v41, v42, v43
	v_cvt_pk_bf16_f32 v42, v44, v45
	v_cvt_pk_bf16_f32 v43, v46, v47
	global_store_dwordx4 v3, v[32:35], s[4:5]
	global_store_dwordx4 v3, v[40:43], s[4:5] offset:1024
	v_pk_mul_f32 v[106:107], v[48:49], v[48:49]
	v_pk_mul_f32 v[108:109], v[50:51], v[50:51]
	v_add_f32_e32 v104, v106, v107
	v_add_f32_e32 v104, v104, v108
	v_pk_mul_f32 v[110:111], v[52:53], v[52:53]
	v_add_f32_e32 v104, v104, v109
	v_add_f32_e32 v104, v104, v110
	v_pk_mul_f32 v[112:113], v[54:55], v[54:55]
	v_add_f32_e32 v104, v104, v111
	v_add_f32_e32 v104, v104, v112
	v_add_f32_e32 v104, v104, v113
	v_pk_mul_f32 v[106:107], v[56:57], v[56:57]
	v_pk_mul_f32 v[108:109], v[58:59], v[58:59]
	v_add_f32_e32 v105, v106, v107
	v_add_f32_e32 v105, v105, v108
	v_pk_mul_f32 v[110:111], v[60:61], v[60:61]
	v_add_f32_e32 v105, v105, v109
	v_add_f32_e32 v105, v105, v110
	v_pk_mul_f32 v[112:113], v[62:63], v[62:63]
	v_add_f32_e32 v105, v105, v111
	v_add_f32_e32 v105, v105, v112
	v_add_f32_e32 v105, v105, v113
	v_add_f32_e32 v97, v104, v105
	v_cvt_pk_bf16_f32 v48, v48, v49
	v_cvt_pk_bf16_f32 v49, v50, v51
	v_cvt_pk_bf16_f32 v50, v52, v53
	v_cvt_pk_bf16_f32 v51, v54, v55
	v_cvt_pk_bf16_f32 v56, v56, v57
	v_cvt_pk_bf16_f32 v57, v58, v59
	v_cvt_pk_bf16_f32 v58, v60, v61
	v_cvt_pk_bf16_f32 v59, v62, v63
	global_store_dwordx4 v3, v[48:51], s[50:51]
	global_store_dwordx4 v3, v[56:59], s[50:51] offset:1024
	v_pk_mul_f32 v[106:107], v[64:65], v[64:65]
	v_pk_mul_f32 v[108:109], v[66:67], v[66:67]
	v_add_f32_e32 v104, v106, v107
	v_add_f32_e32 v104, v104, v108
	v_pk_mul_f32 v[110:111], v[68:69], v[68:69]
	v_add_f32_e32 v104, v104, v109
	v_add_f32_e32 v104, v104, v110
	v_pk_mul_f32 v[112:113], v[70:71], v[70:71]
	v_add_f32_e32 v104, v104, v111
	v_add_f32_e32 v104, v104, v112
	v_add_f32_e32 v104, v104, v113
	v_pk_mul_f32 v[106:107], v[72:73], v[72:73]
	v_pk_mul_f32 v[108:109], v[74:75], v[74:75]
	v_add_f32_e32 v105, v106, v107
	v_add_f32_e32 v105, v105, v108
	v_pk_mul_f32 v[110:111], v[76:77], v[76:77]
	v_add_f32_e32 v105, v105, v109
	v_add_f32_e32 v105, v105, v110
	v_pk_mul_f32 v[112:113], v[78:79], v[78:79]
	v_add_f32_e32 v105, v105, v111
	v_add_f32_e32 v105, v105, v112
	v_add_f32_e32 v105, v105, v113
	v_add_f32_e32 v98, v104, v105
	v_cvt_pk_bf16_f32 v64, v64, v65
	v_cvt_pk_bf16_f32 v65, v66, v67
	v_cvt_pk_bf16_f32 v66, v68, v69
	v_cvt_pk_bf16_f32 v67, v70, v71
	v_cvt_pk_bf16_f32 v72, v72, v73
	v_cvt_pk_bf16_f32 v73, v74, v75
	v_cvt_pk_bf16_f32 v74, v76, v77
	v_cvt_pk_bf16_f32 v75, v78, v79
	global_store_dwordx4 v3, v[64:67], s[18:19]
	global_store_dwordx4 v3, v[72:75], s[18:19] offset:1024
	v_pk_mul_f32 v[106:107], v[80:81], v[80:81]
	v_pk_mul_f32 v[108:109], v[82:83], v[82:83]
	v_add_f32_e32 v104, v106, v107
	v_add_f32_e32 v104, v104, v108
	v_pk_mul_f32 v[110:111], v[84:85], v[84:85]
	v_add_f32_e32 v104, v104, v109
	v_add_f32_e32 v104, v104, v110
	v_pk_mul_f32 v[112:113], v[86:87], v[86:87]
	v_add_f32_e32 v104, v104, v111
	v_add_f32_e32 v104, v104, v112
	v_add_f32_e32 v104, v104, v113
	v_pk_mul_f32 v[106:107], v[88:89], v[88:89]
	v_pk_mul_f32 v[108:109], v[90:91], v[90:91]
	v_add_f32_e32 v105, v106, v107
	v_add_f32_e32 v105, v105, v108
	v_pk_mul_f32 v[110:111], v[92:93], v[92:93]
	v_add_f32_e32 v105, v105, v109
	v_add_f32_e32 v105, v105, v110
	v_pk_mul_f32 v[112:113], v[94:95], v[94:95]
	v_add_f32_e32 v105, v105, v111
	v_add_f32_e32 v105, v105, v112
	v_add_f32_e32 v105, v105, v113
	v_add_f32_e32 v99, v104, v105
	v_cvt_pk_bf16_f32 v80, v80, v81
	v_cvt_pk_bf16_f32 v81, v82, v83
	v_cvt_pk_bf16_f32 v82, v84, v85
	v_cvt_pk_bf16_f32 v83, v86, v87
	v_cvt_pk_bf16_f32 v88, v88, v89
	v_cvt_pk_bf16_f32 v89, v90, v91
	v_cvt_pk_bf16_f32 v90, v92, v93
	v_cvt_pk_bf16_f32 v91, v94, v95
	global_store_dwordx4 v3, v[80:83], s[30:31]
	global_store_dwordx4 v3, v[88:91], s[30:31] offset:1024
	ds_bpermute_b32 v100, v10, v96
	ds_bpermute_b32 v101, v10, v97
	ds_bpermute_b32 v102, v10, v98
	ds_bpermute_b32 v103, v10, v99
	s_waitcnt lgkmcnt(0)
	v_add_f32_e32 v96, v96, v100
	v_add_f32_e32 v97, v97, v101
	v_add_f32_e32 v98, v98, v102
	v_add_f32_e32 v99, v99, v103
	ds_bpermute_b32 v100, v11, v96
	ds_bpermute_b32 v101, v11, v97
	ds_bpermute_b32 v102, v11, v98
	ds_bpermute_b32 v103, v11, v99
	s_waitcnt lgkmcnt(0)
	v_add_f32_e32 v96, v96, v100
	v_add_f32_e32 v97, v97, v101
	v_add_f32_e32 v98, v98, v102
	v_add_f32_e32 v99, v99, v103
	ds_bpermute_b32 v100, v12, v96
	ds_bpermute_b32 v101, v12, v97
	ds_bpermute_b32 v102, v12, v98
	ds_bpermute_b32 v103, v12, v99
	s_waitcnt lgkmcnt(0)
	v_add_f32_e32 v96, v96, v100
	v_add_f32_e32 v97, v97, v101
	v_add_f32_e32 v98, v98, v102
	v_add_f32_e32 v99, v99, v103
	ds_bpermute_b32 v100, v13, v96
	ds_bpermute_b32 v101, v13, v97
	ds_bpermute_b32 v102, v13, v98
	ds_bpermute_b32 v103, v13, v99
	s_waitcnt lgkmcnt(0)
	v_add_f32_e32 v96, v96, v100
	v_add_f32_e32 v97, v97, v101
	v_add_f32_e32 v98, v98, v102
	v_add_f32_e32 v99, v99, v103
	ds_bpermute_b32 v100, v14, v96
	ds_bpermute_b32 v101, v14, v97
	ds_bpermute_b32 v102, v14, v98
	ds_bpermute_b32 v103, v14, v99
	s_waitcnt lgkmcnt(0)
	v_add_f32_e32 v96, v96, v100
	v_add_f32_e32 v97, v97, v101
	v_add_f32_e32 v98, v98, v102
	v_add_f32_e32 v99, v99, v103
	ds_bpermute_b32 v100, v15, v96
	ds_bpermute_b32 v101, v15, v97
	ds_bpermute_b32 v102, v15, v98
	ds_bpermute_b32 v103, v15, v99
	s_waitcnt lgkmcnt(0)
	v_add_f32_e32 v96, v96, v100
	v_add_f32_e32 v97, v97, v101
	v_add_f32_e32 v98, v98, v102
	v_add_f32_e32 v99, v99, v103
	s_mov_b64 s[48:49], exec
	s_and_b64 exec, exec, s[44:45]
	s_lshl_b32 s12, s14, 2
	s_add_u32 s0, s42, s12
	s_addc_u32 s1, s43, 0
	global_store_dword v129, v96, s[0:1]
	s_lshl_b32 s12, s47, 2
	s_add_u32 s0, s42, s12
	s_addc_u32 s1, s43, 0
	global_store_dword v129, v97, s[0:1]
	s_lshl_b32 s12, s34, 2
	s_add_u32 s0, s42, s12
	s_addc_u32 s1, s43, 0
	global_store_dword v129, v98, s[0:1]
	s_lshl_b32 s12, s35, 2
	s_add_u32 s0, s42, s12
	s_addc_u32 s1, s43, 0
	global_store_dword v129, v99, s[0:1]
	s_mov_b64 exec, s[48:49]
	s_mov_b32 s14, s15
	s_cmp_lt_u32 s14, 0xc000
	s_cbranch_scc1 .Ln0_loop
	v_readlane_b32 s36, v252, 10
	v_readlane_b32 s37, v252, 11
	v_readlane_b32 s38, v252, 12
	v_readlane_b32 s39, v252, 13
	v_readlane_b32 s40, v252, 14
	v_readlane_b32 s41, v252, 15
	v_readlane_b32 s42, v252, 16
	v_readlane_b32 s43, v252, 17
	v_readlane_b32 s44, v252, 18
	v_readlane_b32 s45, v252, 19
	v_readlane_b32 s46, v252, 20
	v_readlane_b32 s47, v252, 21
	v_readlane_b32 s48, v252, 22
	v_readlane_b32 s49, v252, 23
	v_readlane_b32 s50, v252, 24
	v_readlane_b32 s51, v252, 25
